# P3 q-up epilogue: cos/sin rows of all eight row groups touched once at the epilogue start (cache warm-up) so the sixteen serialized rope stages hit L2
# speedup vs baseline: 1.0100x; 1.0100x over previous
.LBB0_508:
	s_lshl_b32 s2, s6, 8
	v_lshl_add_u32 v146, s48, 8, v155
	s_or_b32 s48, s2, s74
	s_mul_hi_i32 s2, s48, 0x2aaaaaab
	s_lshr_b32 s3, s2, 31
	s_lshr_b32 s2, s2, 4
	s_add_i32 s2, s2, s3
	s_mulk_i32 s2, 0x60
	s_sub_i32 s6, s48, s2
	v_ashrrev_i32_e32 v147, 31, v146
	s_cmp_eq_u32 s6, 64
	v_pk_mul_f32 v[150:151], v[122:123], s[38:39] op_sel_hi:[1,0]
	v_lshlrev_b64 v[122:123], 6, v[146:147]
	s_cselect_b64 s[2:3], -1, 0
	s_cmp_lg_u32 s6, 64
	v_pk_mul_f32 v[126:127], v[126:127], s[38:39] op_sel_hi:[1,0]
	v_pk_mul_f32 v[148:149], v[124:125], s[38:39] op_sel_hi:[1,0]
	v_pk_mul_f32 v[152:153], v[120:121], s[38:39] op_sel_hi:[1,0]
	v_lshl_add_u64 v[120:121], v[138:139], 0, v[122:123]
	v_lshl_add_u64 v[122:123], v[140:141], 0, v[122:123]
	s_mov_b64 vcc, 0x1000
	s_nop 0
	v_lshl_add_u64 v[188:189], v[120:121], 0, vcc
	v_lshl_add_u64 v[190:191], v[122:123], 0, vcc
	global_load_dwordx4 v[184:187], v[120:121], off offset:1024
	global_load_dwordx4 v[184:187], v[120:121], off offset:1040
	global_load_dwordx4 v[184:187], v[120:121], off offset:2048
	global_load_dwordx4 v[184:187], v[120:121], off offset:2064
	global_load_dwordx4 v[184:187], v[120:121], off offset:3072
	global_load_dwordx4 v[184:187], v[120:121], off offset:3088
	global_load_dwordx4 v[184:187], v[122:123], off offset:1024
	global_load_dwordx4 v[184:187], v[122:123], off offset:1040
	global_load_dwordx4 v[184:187], v[122:123], off offset:2048
	global_load_dwordx4 v[184:187], v[122:123], off offset:2064
	global_load_dwordx4 v[184:187], v[122:123], off offset:3072
	global_load_dwordx4 v[184:187], v[122:123], off offset:3088
	global_load_dwordx4 v[184:187], v[188:189], off
	global_load_dwordx4 v[184:187], v[188:189], off offset:16
	global_load_dwordx4 v[184:187], v[188:189], off offset:1024
	global_load_dwordx4 v[184:187], v[188:189], off offset:1040
	global_load_dwordx4 v[184:187], v[188:189], off offset:2048
	global_load_dwordx4 v[184:187], v[188:189], off offset:2064
	global_load_dwordx4 v[184:187], v[188:189], off offset:3072
	global_load_dwordx4 v[184:187], v[188:189], off offset:3088
	global_load_dwordx4 v[184:187], v[190:191], off
	global_load_dwordx4 v[184:187], v[190:191], off offset:16
	global_load_dwordx4 v[184:187], v[190:191], off offset:1024
	global_load_dwordx4 v[184:187], v[190:191], off offset:1040
	global_load_dwordx4 v[184:187], v[190:191], off offset:2048
	global_load_dwordx4 v[184:187], v[190:191], off offset:2064
	global_load_dwordx4 v[184:187], v[190:191], off offset:3072
	global_load_dwordx4 v[184:187], v[190:191], off offset:3088
	s_cbranch_scc1 .LBB0_510
	global_load_dwordx4 v[162:165], v[122:123], off
	global_load_dwordx4 v[166:169], v[122:123], off offset:16
	global_load_dwordx4 v[170:173], v[120:121], off
	global_load_dwordx4 v[174:177], v[120:121], off offset:16
	v_and_b32_e32 v125, 64, v160
	v_xor_b32_e32 v124, 32, v160
	v_add_u32_e32 v125, 64, v125
	v_cmp_lt_i32_e32 vcc, v124, v125
	s_nop 1
	v_cndmask_b32_e32 v124, v160, v124, vcc
	v_lshlrev_b32_e32 v147, 2, v124
	ds_bpermute_b32 v124, v147, v148
	ds_bpermute_b32 v178, v147, v152
	ds_bpermute_b32 v125, v147, v149
	ds_bpermute_b32 v180, v147, v126
	ds_bpermute_b32 v181, v147, v127
	ds_bpermute_b32 v182, v147, v150
	ds_bpermute_b32 v183, v147, v151
	ds_bpermute_b32 v179, v147, v153
	s_waitcnt vmcnt(0) lgkmcnt(0)
	v_pk_mul_f32 v[164:165], v[164:165], v[180:181]
	v_pk_mul_f32 v[124:125], v[162:163], v[124:125]
	v_pk_mul_f32 v[162:163], v[168:169], v[182:183]
	v_pk_mul_f32 v[166:167], v[166:167], v[178:179]
	v_pk_mul_f32 v[124:125], v[134:135], v[124:125]
	v_pk_mul_f32 v[164:165], v[136:137], v[164:165]
	v_pk_mul_f32 v[166:167], v[134:135], v[166:167]
	v_pk_mul_f32 v[162:163], v[136:137], v[162:163]
	v_pk_fma_f32 v[126:127], v[126:127], v[172:173], v[164:165]
	v_pk_fma_f32 v[148:149], v[148:149], v[170:171], v[124:125]
	v_pk_fma_f32 v[150:151], v[150:151], v[176:177], v[162:163]
	v_pk_fma_f32 v[152:153], v[152:153], v[174:175], v[166:167]
